# phase 0: non-temporal hint on the once-read f32 weight loads (w_in, w_out, w_ffn_out transposes, adaLN w_mod)
# speedup vs baseline: 1.0138x; 1.0093x over previous
.LBB0_57:
	s_andn2_b64 vcc, exec, s[6:7]
	s_cbranch_vccnz .LBB0_59
	s_add_i32 s6, s39, 0xf580
	s_and_b32 s7, s6, 0xffff
	s_mul_i32 s7, s7, 0xba2f
	s_lshr_b32 s7, s7, 21
	s_mul_i32 s8, s7, 44
	s_sub_i32 s6, s6, s8
	s_lshl_b32 s6, s6, 6
	v_mov_b32_e32 v12, v188
	s_and_b32 s8, s6, 0xffc0
	s_lshl_b32 s6, s7, 6
	v_ashrrev_i32_e32 v13, 4, v12
	v_lshlrev_b32_e32 v0, 2, v12
	v_and_b32_e32 v21, 60, v0
	v_add_u32_e32 v0, s8, v13
	v_ashrrev_i32_e32 v1, 31, v0
	v_lshlrev_b64 v[2:3], 12, v[0:1]
	v_add_u32_e32 v0, 32, v0
	v_or_b32_e32 v4, s6, v21
	v_ashrrev_i32_e32 v1, 31, v0
	v_lshl_add_u64 v[2:3], s[86:87], 0, v[2:3]
	v_lshlrev_b32_e32 v10, 2, v4
	v_lshlrev_b64 v[0:1], 12, v[0:1]
	v_lshl_add_u64 v[2:3], v[2:3], 0, v[10:11]
	v_lshl_add_u64 v[0:1], s[86:87], 0, v[0:1]
	v_lshl_add_u64 v[4:5], v[0:1], 0, v[10:11]
	global_load_dwordx4 v[0:3], v[2:3], off nt
	s_nop 0
	global_load_dwordx4 v[28:31], v[4:5], off nt
	v_ashrrev_i32_e32 v10, 3, v12
	v_lshlrev_b32_e32 v12, 3, v12
	v_and_b32_e32 v12, 56, v12
	v_mul_lo_u32 v13, v13, s4
	v_lshlrev_b32_e32 v22, 2, v10
	v_lshlrev_b32_e32 v21, 2, v21
	v_mul_u32_u24_e32 v23, 0x110, v12
	v_add3_u32 v13, 0, v21, v13
	v_add3_u32 v21, 0, v23, v22
	v_mov_b64_e32 v[4:5], s[18:19]
	s_movk_i32 s7, 0x1600
	v_add_u32_e32 v10, s6, v10
	v_add_u32_e32 v22, 0x400, v21
	v_mad_i64_i32 v[4:5], s[6:7], v10, s7, v[4:5]
	v_lshlrev_b32_e32 v10, 1, v12
	s_lshl_b32 s30, s8, 1
	v_lshl_add_u64 v[4:5], v[4:5], 0, s[30:31]
	v_lshl_add_u64 v[4:5], v[4:5], 0, v[10:11]
	s_waitcnt vmcnt(1)
	ds_write_b128 v13, v[0:3]
	s_waitcnt vmcnt(0)
	ds_write_b128 v13, v[28:31] offset:8704
	s_waitcnt lgkmcnt(0)
	s_barrier
	ds_read2_b32 v[0:1], v21 offset1:68
	ds_read2_b32 v[2:3], v21 offset0:136 offset1:204
	ds_read2_b32 v[12:13], v22 offset0:16 offset1:84
	ds_read2_b32 v[22:23], v22 offset0:152 offset1:220
	s_waitcnt lgkmcnt(3)
	v_cvt_pk_bf16_f32 v0, v0, v1
	s_waitcnt lgkmcnt(2)
	v_cvt_pk_bf16_f32 v1, v2, v3
	s_waitcnt lgkmcnt(1)
	v_cvt_pk_bf16_f32 v2, v12, v13
	s_waitcnt lgkmcnt(0)
	v_cvt_pk_bf16_f32 v3, v22, v23
	global_store_dwordx4 v[4:5], v[0:3], off
	s_barrier

.LBB0_63:
	s_andn2_b64 vcc, exec, s[6:7]
	s_cbranch_vccnz .LBB0_65
	s_lshl_b32 s6, s39, 6
	v_mov_b32_e32 v12, v188
	s_and_b32 s6, s6, 0x3c0
	s_lshl_b32 s7, s39, 2
	v_ashrrev_i32_e32 v13, 4, v12
	v_lshlrev_b32_e32 v0, 2, v12
	v_and_b32_e32 v21, 60, v0
	v_add_u32_e32 v0, s6, v13
	s_and_b32 s7, s7, 0x1fc0
	v_ashrrev_i32_e32 v1, 31, v0
	s_addk_i32 s7, 0xf000
	v_lshlrev_b64 v[2:3], 12, v[0:1]
	v_add_u32_e32 v0, 32, v0
	v_or_b32_e32 v10, s7, v21
	v_ashrrev_i32_e32 v1, 31, v0
	v_lshl_add_u64 v[2:3], s[80:81], 0, v[2:3]
	v_lshlrev_b64 v[4:5], 2, v[10:11]
	v_lshlrev_b64 v[0:1], 12, v[0:1]
	v_lshl_add_u64 v[2:3], v[2:3], 0, v[4:5]
	v_lshl_add_u64 v[0:1], s[80:81], 0, v[0:1]
	v_lshl_add_u64 v[4:5], v[0:1], 0, v[4:5]
	global_load_dwordx4 v[0:3], v[2:3], off nt
	s_nop 0
	global_load_dwordx4 v[28:31], v[4:5], off nt
	v_lshlrev_b32_e32 v5, 3, v12
	v_ashrrev_i32_e32 v4, 3, v12
	v_and_b32_e32 v12, 56, v5
	v_mul_lo_u32 v10, v13, s4
	v_lshlrev_b32_e32 v13, 2, v4
	v_mul_u32_u24_e32 v22, 0x110, v12
	v_lshlrev_b32_e32 v21, 2, v21
	v_add3_u32 v13, 0, v22, v13
	v_add3_u32 v21, 0, v21, v10
	v_add_u32_e32 v22, 0x400, v13
	v_add_u32_e32 v4, s7, v4
	v_lshlrev_b32_e32 v10, 1, v12
	v_ashrrev_i32_e32 v5, 31, v4
	v_lshlrev_b64 v[4:5], 11, v[4:5]
	s_lshl_b32 s30, s6, 1
	v_lshl_add_u64 v[4:5], s[22:23], 0, v[4:5]
	v_lshl_add_u64 v[4:5], v[4:5], 0, s[30:31]
	v_lshl_add_u64 v[4:5], v[4:5], 0, v[10:11]
	s_waitcnt vmcnt(1)
	ds_write_b128 v21, v[0:3]
	s_waitcnt vmcnt(0)
	ds_write_b128 v21, v[28:31] offset:8704
	s_waitcnt lgkmcnt(0)
	s_barrier
	ds_read2_b32 v[0:1], v13 offset1:68
	ds_read2_b32 v[2:3], v13 offset0:136 offset1:204
	ds_read2_b32 v[12:13], v22 offset0:16 offset1:84
	ds_read2_b32 v[22:23], v22 offset0:152 offset1:220
	s_waitcnt lgkmcnt(3)
	v_cvt_pk_bf16_f32 v0, v0, v1
	s_waitcnt lgkmcnt(2)
	v_cvt_pk_bf16_f32 v1, v2, v3
	s_waitcnt lgkmcnt(1)
	v_cvt_pk_bf16_f32 v2, v12, v13
	s_waitcnt lgkmcnt(0)
	v_cvt_pk_bf16_f32 v3, v22, v23
	global_store_dwordx4 v[4:5], v[0:3], off
	s_barrier

.LBB0_66:
	s_andn2_b64 vcc, exec, s[6:7]
	s_cbranch_vccnz .LBB0_72
	s_lshl_b32 s6, s39, 6
	s_and_b32 s10, s6, 0x3c0
	s_lshl_b32 s6, s39, 2
	v_mov_b32_e32 v12, v188
	s_and_b32 s11, s6, 0xfc0
	s_addk_i32 s11, 0xfd00
	v_lshlrev_b32_e32 v0, 2, v12
	v_and_b32_e32 v1, 60, v0
	v_or_b32_e32 v0, s11, v1
	s_cmpk_lt_u32 s11, 0x600
	s_movk_i32 s6, 0xc20
	s_cselect_b64 vcc, -1, 0
	s_cmpk_lt_u32 s11, 0xc00
	v_add_u32_e32 v2, 0xfffffa00, v0
	v_cmp_gt_u32_e64 s[6:7], s6, v0
	v_add_u32_e32 v3, 32, v0
	v_ashrrev_i32_e32 v13, 4, v12
	v_cndmask_b32_e64 v2, -1, v2, s[6:7]
	s_cselect_b64 s[6:7], -1, 0
	v_cndmask_b32_e64 v2, v2, v3, s[6:7]
	v_cndmask_b32_e32 v10, v2, v0, vcc
	v_cmp_lt_i32_e32 vcc, -1, v10
	v_mov_b32_e32 v0, 0
	v_mov_b32_e32 v2, 0
	v_mov_b32_e32 v3, 0
	v_mov_b32_e32 v4, 0
	v_mov_b32_e32 v5, 0
	s_and_saveexec_b64 s[6:7], vcc
	s_cbranch_execz .LBB0_69
	v_add_u32_e32 v4, s10, v13
	v_mov_b64_e32 v[2:3], s[54:55]
	v_mad_i64_i32 v[2:3], s[8:9], v4, s38, v[2:3]
	v_lshl_add_u64 v[2:3], v[10:11], 2, v[2:3]
	global_load_dwordx4 v[2:5], v[2:3], off nt
.LBB0_69:
	s_or_b64 exec, exec, s[6:7]
	s_cmpk_lt_u32 s11, 0x100
	s_waitcnt vmcnt(0)
	v_pk_mul_f32 v[22:23], v[2:3], s[34:35] op_sel_hi:[1,0]
	v_pk_mul_f32 v[28:29], v[4:5], s[34:35] op_sel_hi:[1,0]
	s_cselect_b64 s[6:7], -1, 0
	v_lshl_add_u32 v1, v1, 2, 0
	v_cndmask_b32_e64 v30, v4, v28, s[6:7]
	v_cndmask_b32_e64 v28, v2, v22, s[6:7]
	v_mul_lo_u32 v2, v13, s4
	v_cndmask_b32_e64 v31, v5, v29, s[6:7]
	v_cndmask_b32_e64 v29, v3, v23, s[6:7]
	v_add_u32_e32 v4, v1, v2
	v_mov_b32_e32 v1, 0
	v_mov_b32_e32 v2, 0
	v_mov_b32_e32 v3, 0
	ds_write_b128 v4, v[28:31]
	s_and_saveexec_b64 s[8:9], vcc
	s_cbranch_execz .LBB0_71
	v_add3_u32 v2, v13, s10, 32
	v_mov_b64_e32 v[0:1], s[54:55]
	v_mad_i64_i32 v[0:1], s[36:37], v2, s38, v[0:1]
	v_lshl_add_u64 v[0:1], v[10:11], 2, v[0:1]
	global_load_dwordx4 v[0:3], v[0:1], off nt

.LBB0_73:
	v_mov_b32_e32 v0, v188
	v_lshlrev_b32_e32 v21, 2, v0
	s_mov_b64 s[10:11], s[42:43]
	global_load_dword v94, v21, s[10:11]
	global_load_dword v95, v21, s[10:11] offset:2048
	s_add_u32 s10, s10, 0x1000
	s_addc_u32 s11, s11, 0
	global_load_dword v96, v21, s[10:11]
	global_load_dword v97, v21, s[10:11] offset:2048
	s_add_u32 s10, s10, 0x1000
	s_addc_u32 s11, s11, 0
	global_load_dword v98, v21, s[10:11]
	global_load_dword v99, v21, s[10:11] offset:2048
	s_add_u32 s10, s10, 0x1000
	s_addc_u32 s11, s11, 0
	global_load_dword v100, v21, s[10:11]
	global_load_dword v101, v21, s[10:11] offset:2048
	global_load_dword v102, v21, s[46:47]
	global_load_dword v103, v21, s[46:47] offset:2048
	v_and_b32_e32 v1, 31, v0
	v_lshrrev_b32_e32 v10, 5, v0
	v_add_u32_e32 v2, s96, v1
	v_lshlrev_b32_e32 v2, 2, v2
	v_mul_u32_u24_e32 v3, 0x180000, v10
	v_add_u32_e32 v3, v3, v2
	s_sub_u32 s8, s26, 0x2a000
	s_subb_u32 s9, s27, 0
	global_load_dword v132, v3, s[8:9] nt
	s_add_u32 s8, s8, 0x6000
	s_addc_u32 s9, s9, 0
	global_load_dword v133, v3, s[8:9] nt
	s_add_u32 s8, s8, 0x6000
	s_addc_u32 s9, s9, 0
	global_load_dword v134, v3, s[8:9] nt
	s_add_u32 s8, s8, 0x6000
	s_addc_u32 s9, s9, 0
	global_load_dword v135, v3, s[8:9] nt
	s_add_u32 s8, s8, 0x6000
	s_addc_u32 s9, s9, 0
	global_load_dword v136, v3, s[8:9] nt
	s_add_u32 s8, s8, 0x6000
	s_addc_u32 s9, s9, 0
	global_load_dword v137, v3, s[8:9] nt
	s_add_u32 s8, s8, 0x6000
	s_addc_u32 s9, s9, 0
	global_load_dword v138, v3, s[8:9] nt
	s_add_u32 s8, s8, 0x6000
	s_addc_u32 s9, s9, 0
	global_load_dword v139, v3, s[8:9] nt
	s_add_u32 s8, s8, 0x6000
	s_addc_u32 s9, s9, 0
	global_load_dword v140, v3, s[8:9] nt
	s_add_u32 s8, s8, 0x6000
	s_addc_u32 s9, s9, 0
	global_load_dword v141, v3, s[8:9] nt
	s_add_u32 s8, s8, 0x6000
	s_addc_u32 s9, s9, 0
	global_load_dword v142, v3, s[8:9] nt
	s_add_u32 s8, s8, 0x6000
	s_addc_u32 s9, s9, 0
	global_load_dword v143, v3, s[8:9] nt
	s_add_u32 s8, s8, 0x6000
	s_addc_u32 s9, s9, 0
	global_load_dword v144, v3, s[8:9] nt
	s_add_u32 s8, s8, 0x6000
	s_addc_u32 s9, s9, 0
	global_load_dword v145, v3, s[8:9] nt
	s_add_u32 s8, s8, 0x6000
	s_addc_u32 s9, s9, 0
	global_load_dword v146, v3, s[8:9] nt
	s_add_u32 s8, s8, 0x6000
	s_addc_u32 s9, s9, 0
	global_load_dword v147, v3, s[8:9] nt
	s_add_u32 s8, s8, 0x6000
	s_addc_u32 s9, s9, 0
	global_load_dword v148, v3, s[8:9] nt
	s_add_u32 s8, s8, 0x6000
	s_addc_u32 s9, s9, 0
	global_load_dword v149, v3, s[8:9] nt
	s_add_u32 s8, s8, 0x6000
	s_addc_u32 s9, s9, 0
	global_load_dword v150, v3, s[8:9] nt
	s_add_u32 s8, s8, 0x6000
	s_addc_u32 s9, s9, 0
	global_load_dword v151, v3, s[8:9] nt
	s_add_u32 s8, s8, 0x6000
	s_addc_u32 s9, s9, 0
	global_load_dword v152, v3, s[8:9] nt
	s_add_u32 s8, s8, 0x6000
	s_addc_u32 s9, s9, 0
	global_load_dword v153, v3, s[8:9] nt
	s_add_u32 s8, s8, 0x6000
	s_addc_u32 s9, s9, 0
	global_load_dword v154, v3, s[8:9] nt
	s_add_u32 s8, s8, 0x6000
	s_addc_u32 s9, s9, 0
	global_load_dword v155, v3, s[8:9] nt
	s_add_u32 s8, s8, 0x6000
	s_addc_u32 s9, s9, 0
	global_load_dword v156, v3, s[8:9] nt
	s_add_u32 s8, s8, 0x6000
	s_addc_u32 s9, s9, 0
	global_load_dword v157, v3, s[8:9] nt
	s_add_u32 s8, s8, 0x6000
	s_addc_u32 s9, s9, 0
	global_load_dword v158, v3, s[8:9] nt
	s_add_u32 s8, s8, 0x6000
	s_addc_u32 s9, s9, 0
	global_load_dword v159, v3, s[8:9] nt
	s_add_u32 s8, s8, 0x6000
	s_addc_u32 s9, s9, 0
	global_load_dword v160, v3, s[8:9] nt
	s_add_u32 s8, s8, 0x6000
	s_addc_u32 s9, s9, 0
	global_load_dword v161, v3, s[8:9] nt
	s_add_u32 s8, s8, 0x6000
	s_addc_u32 s9, s9, 0
	global_load_dword v162, v3, s[8:9] nt
	s_add_u32 s8, s8, 0x6000
	s_addc_u32 s9, s9, 0
	global_load_dword v163, v3, s[8:9] nt
	s_add_u32 s8, s8, 0x6000
	s_addc_u32 s9, s9, 0
	s_waitcnt vmcnt(31)
	v_mul_f32_e32 v104, 0xbfb8aa3b, v94
	v_mul_f32_e32 v105, 0xbfb8aa3b, v95
	v_mul_f32_e32 v106, 0xbfb8aa3b, v96
	v_mul_f32_e32 v107, 0xbfb8aa3b, v97
	v_mul_f32_e32 v108, 0xbfb8aa3b, v98
	v_mul_f32_e32 v109, 0xbfb8aa3b, v99
	v_mul_f32_e32 v110, 0xbfb8aa3b, v100
	v_mul_f32_e32 v111, 0xbfb8aa3b, v101
	v_mul_f32_e32 v112, 0xbfb8aa3b, v102
	v_mul_f32_e32 v113, 0xbfb8aa3b, v103
	v_exp_f32_e32 v104, v104
	v_exp_f32_e32 v105, v105
	v_exp_f32_e32 v106, v106
	v_exp_f32_e32 v107, v107
	v_exp_f32_e32 v108, v108
	v_exp_f32_e32 v109, v109
	v_exp_f32_e32 v110, v110
	v_exp_f32_e32 v111, v111
	v_exp_f32_e32 v112, v112
	v_exp_f32_e32 v113, v113
	v_add_f32_e32 v104, 1.0, v104
	v_add_f32_e32 v105, 1.0, v105
	v_add_f32_e32 v106, 1.0, v106
	v_add_f32_e32 v107, 1.0, v107
	v_add_f32_e32 v108, 1.0, v108
	v_add_f32_e32 v109, 1.0, v109
	v_add_f32_e32 v110, 1.0, v110
	v_add_f32_e32 v111, 1.0, v111
	v_add_f32_e32 v112, 1.0, v112
	v_add_f32_e32 v113, 1.0, v113
	v_rcp_f32_e32 v104, v104
	v_rcp_f32_e32 v105, v105
	v_rcp_f32_e32 v106, v106
	v_rcp_f32_e32 v107, v107
	v_rcp_f32_e32 v108, v108
	v_rcp_f32_e32 v109, v109
	v_rcp_f32_e32 v110, v110
	v_rcp_f32_e32 v111, v111
	v_rcp_f32_e32 v112, v112
	v_rcp_f32_e32 v113, v113
	v_mul_f32_e32 v94, v94, v104
	v_mul_f32_e32 v95, v95, v105
	v_mul_f32_e32 v96, v96, v106
	v_mul_f32_e32 v97, v97, v107
	v_mul_f32_e32 v98, v98, v108
	v_mul_f32_e32 v99, v99, v109
	v_mul_f32_e32 v100, v100, v110
	v_mul_f32_e32 v101, v101, v111
	v_mul_f32_e32 v102, v102, v112
	v_mul_f32_e32 v103, v103, v113
	ds_write_b32 v21, v94
	ds_write_b32 v21, v95 offset:2048
	ds_write_b32 v21, v96 offset:4096
	ds_write_b32 v21, v97 offset:6144
	ds_write_b32 v21, v98 offset:8192
	ds_write_b32 v21, v99 offset:10240
	ds_write_b32 v21, v100 offset:12288
	ds_write_b32 v21, v101 offset:14336
	ds_write_b32 v21, v102 offset:16384
	ds_write_b32 v21, v103 offset:18432
	global_load_dword v164, v3, s[8:9] nt
	s_add_u32 s8, s8, 0x6000
	s_addc_u32 s9, s9, 0
	global_load_dword v165, v3, s[8:9] nt
	s_add_u32 s8, s8, 0x6000
	s_addc_u32 s9, s9, 0
	global_load_dword v166, v3, s[8:9] nt
	s_add_u32 s8, s8, 0x6000
	s_addc_u32 s9, s9, 0
	global_load_dword v167, v3, s[8:9] nt
	s_add_u32 s8, s8, 0x6000
	s_addc_u32 s9, s9, 0
	global_load_dword v168, v3, s[8:9] nt
	s_add_u32 s8, s8, 0x6000
	s_addc_u32 s9, s9, 0
	global_load_dword v169, v3, s[8:9] nt
	s_add_u32 s8, s8, 0x6000
	s_addc_u32 s9, s9, 0
	global_load_dword v170, v3, s[8:9] nt
	s_add_u32 s8, s8, 0x6000
	s_addc_u32 s9, s9, 0
	global_load_dword v171, v3, s[8:9] nt
	s_add_u32 s8, s8, 0x6000
	s_addc_u32 s9, s9, 0
	global_load_dword v172, v3, s[8:9] nt
	s_add_u32 s8, s8, 0x6000
	s_addc_u32 s9, s9, 0
	global_load_dword v173, v3, s[8:9] nt
	s_add_u32 s8, s8, 0x6000
	s_addc_u32 s9, s9, 0
	global_load_dword v174, v3, s[8:9] nt
	s_add_u32 s8, s8, 0x6000
	s_addc_u32 s9, s9, 0
	global_load_dword v175, v3, s[8:9] nt
	s_add_u32 s8, s8, 0x6000
	s_addc_u32 s9, s9, 0
	global_load_dword v176, v3, s[8:9] nt
	s_add_u32 s8, s8, 0x6000
	s_addc_u32 s9, s9, 0
	global_load_dword v177, v3, s[8:9] nt
	s_add_u32 s8, s8, 0x6000
	s_addc_u32 s9, s9, 0
	global_load_dword v178, v3, s[8:9] nt
	s_add_u32 s8, s8, 0x6000
	s_addc_u32 s9, s9, 0
	global_load_dword v179, v3, s[8:9] nt
	s_add_u32 s8, s8, 0x6000
	s_addc_u32 s9, s9, 0
	global_load_dword v180, v3, s[8:9] nt
	s_add_u32 s8, s8, 0x6000
	s_addc_u32 s9, s9, 0
	global_load_dword v181, v3, s[8:9] nt
	s_add_u32 s8, s8, 0x6000
	s_addc_u32 s9, s9, 0
	global_load_dword v182, v3, s[8:9] nt
	s_add_u32 s8, s8, 0x6000
	s_addc_u32 s9, s9, 0
	global_load_dword v183, v3, s[8:9] nt
	s_add_u32 s8, s8, 0x6000
	s_addc_u32 s9, s9, 0
	global_load_dword v184, v3, s[8:9] nt
	s_add_u32 s8, s8, 0x6000
	s_addc_u32 s9, s9, 0
	global_load_dword v185, v3, s[8:9] nt
	s_add_u32 s8, s8, 0x6000
	s_addc_u32 s9, s9, 0
	global_load_dword v186, v3, s[8:9] nt
	s_add_u32 s8, s8, 0x6000
	s_addc_u32 s9, s9, 0
	global_load_dword v187, v3, s[8:9] nt
	s_add_u32 s8, s8, 0x6000
	s_addc_u32 s9, s9, 0
	global_load_dword v192, v3, s[8:9] nt
	s_add_u32 s8, s8, 0x6000
	s_addc_u32 s9, s9, 0
	global_load_dword v193, v3, s[8:9] nt
	s_add_u32 s8, s8, 0x6000
	s_addc_u32 s9, s9, 0
	global_load_dword v194, v3, s[8:9] nt
	s_add_u32 s8, s8, 0x6000
	s_addc_u32 s9, s9, 0
	global_load_dword v195, v3, s[8:9] nt
	s_add_u32 s8, s8, 0x6000
	s_addc_u32 s9, s9, 0
	global_load_dword v196, v3, s[8:9] nt
	s_add_u32 s8, s8, 0x6000
	s_addc_u32 s9, s9, 0
	global_load_dword v197, v3, s[8:9] nt
	s_add_u32 s8, s8, 0x6000
	s_addc_u32 s9, s9, 0
	global_load_dword v198, v3, s[8:9] nt
	s_add_u32 s8, s8, 0x6000
	s_addc_u32 s9, s9, 0
	global_load_dword v199, v3, s[8:9] nt
	s_add_u32 s8, s8, 0x6000
	s_addc_u32 s9, s9, 0
	v_lshlrev_b32_e32 v23, 8, v10
	s_waitcnt lgkmcnt(0)
	s_barrier
	ds_read_b128 v[28:31], v23
	ds_read_b128 v[32:35], v23 offset:4096
	ds_read_b128 v[36:39], v23 offset:8192
	ds_read_b128 v[40:43], v23 offset:12288
	ds_read_b128 v[44:47], v23 offset:16384
	ds_read_b128 v[74:77], v23 offset:16
	ds_read_b128 v[78:81], v23 offset:4112
	ds_read_b128 v[82:85], v23 offset:8208
	ds_read_b128 v[86:89], v23 offset:12304
	ds_read_b128 v[90:93], v23 offset:16400
	s_waitcnt vmcnt(60) lgkmcnt(5)
	v_mul_f32_e32 v4, v28, v132
	v_mul_f32_e32 v5, v32, v132
	v_mul_f32_e32 v12, v36, v132
	v_mul_f32_e32 v13, v40, v132
	v_mul_f32_e32 v22, v44, v132
	v_fmac_f32_e32 v4, v29, v133
	v_fmac_f32_e32 v5, v33, v133
	v_fmac_f32_e32 v12, v37, v133
	v_fmac_f32_e32 v13, v41, v133
	v_fmac_f32_e32 v22, v45, v133
	v_fmac_f32_e32 v4, v30, v134
	v_fmac_f32_e32 v5, v34, v134
	v_fmac_f32_e32 v12, v38, v134
	v_fmac_f32_e32 v13, v42, v134
	v_fmac_f32_e32 v22, v46, v134
	v_fmac_f32_e32 v4, v31, v135
	v_fmac_f32_e32 v5, v35, v135
	v_fmac_f32_e32 v12, v39, v135
	v_fmac_f32_e32 v13, v43, v135
	v_fmac_f32_e32 v22, v47, v135
	ds_read_b128 v[28:31], v23 offset:32
	ds_read_b128 v[32:35], v23 offset:4128
	ds_read_b128 v[36:39], v23 offset:8224
	ds_read_b128 v[40:43], v23 offset:12320
	ds_read_b128 v[44:47], v23 offset:16416
	s_waitcnt vmcnt(56) lgkmcnt(5)
	v_fmac_f32_e32 v4, v74, v136
	v_fmac_f32_e32 v5, v78, v136
	v_fmac_f32_e32 v12, v82, v136
	v_fmac_f32_e32 v13, v86, v136
	v_fmac_f32_e32 v22, v90, v136
	v_fmac_f32_e32 v4, v75, v137
	v_fmac_f32_e32 v5, v79, v137
	v_fmac_f32_e32 v12, v83, v137
	v_fmac_f32_e32 v13, v87, v137
	v_fmac_f32_e32 v22, v91, v137
	v_fmac_f32_e32 v4, v76, v138
	v_fmac_f32_e32 v5, v80, v138
	v_fmac_f32_e32 v12, v84, v138
	v_fmac_f32_e32 v13, v88, v138
	v_fmac_f32_e32 v22, v92, v138
	v_fmac_f32_e32 v4, v77, v139
	v_fmac_f32_e32 v5, v81, v139
	v_fmac_f32_e32 v12, v85, v139
	v_fmac_f32_e32 v13, v89, v139
	v_fmac_f32_e32 v22, v93, v139
	ds_read_b128 v[74:77], v23 offset:48
	ds_read_b128 v[78:81], v23 offset:4144
	ds_read_b128 v[82:85], v23 offset:8240
	ds_read_b128 v[86:89], v23 offset:12336
	ds_read_b128 v[90:93], v23 offset:16432
	s_waitcnt vmcnt(52) lgkmcnt(5)
	v_fmac_f32_e32 v4, v28, v140
	v_fmac_f32_e32 v5, v32, v140
	v_fmac_f32_e32 v12, v36, v140
	v_fmac_f32_e32 v13, v40, v140
	v_fmac_f32_e32 v22, v44, v140
	v_fmac_f32_e32 v4, v29, v141
	v_fmac_f32_e32 v5, v33, v141
	v_fmac_f32_e32 v12, v37, v141
	v_fmac_f32_e32 v13, v41, v141
	v_fmac_f32_e32 v22, v45, v141
	v_fmac_f32_e32 v4, v30, v142
	v_fmac_f32_e32 v5, v34, v142
	v_fmac_f32_e32 v12, v38, v142
	v_fmac_f32_e32 v13, v42, v142
	v_fmac_f32_e32 v22, v46, v142
	v_fmac_f32_e32 v4, v31, v143
	v_fmac_f32_e32 v5, v35, v143
	v_fmac_f32_e32 v12, v39, v143
	v_fmac_f32_e32 v13, v43, v143
	v_fmac_f32_e32 v22, v47, v143
	ds_read_b128 v[28:31], v23 offset:64
	ds_read_b128 v[32:35], v23 offset:4160
	ds_read_b128 v[36:39], v23 offset:8256
	ds_read_b128 v[40:43], v23 offset:12352
	ds_read_b128 v[44:47], v23 offset:16448
	s_waitcnt vmcnt(48) lgkmcnt(5)
	v_fmac_f32_e32 v4, v74, v144
	v_fmac_f32_e32 v5, v78, v144
	v_fmac_f32_e32 v12, v82, v144
	v_fmac_f32_e32 v13, v86, v144
	v_fmac_f32_e32 v22, v90, v144
	v_fmac_f32_e32 v4, v75, v145
	v_fmac_f32_e32 v5, v79, v145
	v_fmac_f32_e32 v12, v83, v145
	v_fmac_f32_e32 v13, v87, v145
	v_fmac_f32_e32 v22, v91, v145
	v_fmac_f32_e32 v4, v76, v146
	v_fmac_f32_e32 v5, v80, v146
	v_fmac_f32_e32 v12, v84, v146
	v_fmac_f32_e32 v13, v88, v146
	v_fmac_f32_e32 v22, v92, v146
	v_fmac_f32_e32 v4, v77, v147
	v_fmac_f32_e32 v5, v81, v147
	v_fmac_f32_e32 v12, v85, v147
	v_fmac_f32_e32 v13, v89, v147
	v_fmac_f32_e32 v22, v93, v147
	ds_read_b128 v[74:77], v23 offset:80
	ds_read_b128 v[78:81], v23 offset:4176
	ds_read_b128 v[82:85], v23 offset:8272
	ds_read_b128 v[86:89], v23 offset:12368
	ds_read_b128 v[90:93], v23 offset:16464
	s_waitcnt vmcnt(44) lgkmcnt(5)
	v_fmac_f32_e32 v4, v28, v148
	v_fmac_f32_e32 v5, v32, v148
	v_fmac_f32_e32 v12, v36, v148
	v_fmac_f32_e32 v13, v40, v148
	v_fmac_f32_e32 v22, v44, v148
	v_fmac_f32_e32 v4, v29, v149
	v_fmac_f32_e32 v5, v33, v149
	v_fmac_f32_e32 v12, v37, v149
	v_fmac_f32_e32 v13, v41, v149
	v_fmac_f32_e32 v22, v45, v149
	v_fmac_f32_e32 v4, v30, v150
	v_fmac_f32_e32 v5, v34, v150
	v_fmac_f32_e32 v12, v38, v150
	v_fmac_f32_e32 v13, v42, v150
	v_fmac_f32_e32 v22, v46, v150
	v_fmac_f32_e32 v4, v31, v151
	v_fmac_f32_e32 v5, v35, v151
	v_fmac_f32_e32 v12, v39, v151
	v_fmac_f32_e32 v13, v43, v151
	v_fmac_f32_e32 v22, v47, v151
	ds_read_b128 v[28:31], v23 offset:96
	ds_read_b128 v[32:35], v23 offset:4192
	ds_read_b128 v[36:39], v23 offset:8288
	ds_read_b128 v[40:43], v23 offset:12384
	ds_read_b128 v[44:47], v23 offset:16480
	s_waitcnt vmcnt(40) lgkmcnt(5)
	v_fmac_f32_e32 v4, v74, v152
	v_fmac_f32_e32 v5, v78, v152
	v_fmac_f32_e32 v12, v82, v152
	v_fmac_f32_e32 v13, v86, v152
	v_fmac_f32_e32 v22, v90, v152
	v_fmac_f32_e32 v4, v75, v153
	v_fmac_f32_e32 v5, v79, v153
	v_fmac_f32_e32 v12, v83, v153
	v_fmac_f32_e32 v13, v87, v153
	v_fmac_f32_e32 v22, v91, v153
	v_fmac_f32_e32 v4, v76, v154
	v_fmac_f32_e32 v5, v80, v154
	v_fmac_f32_e32 v12, v84, v154
	v_fmac_f32_e32 v13, v88, v154
	v_fmac_f32_e32 v22, v92, v154
	v_fmac_f32_e32 v4, v77, v155
	v_fmac_f32_e32 v5, v81, v155
	v_fmac_f32_e32 v12, v85, v155
	v_fmac_f32_e32 v13, v89, v155
	v_fmac_f32_e32 v22, v93, v155
	ds_read_b128 v[74:77], v23 offset:112
	ds_read_b128 v[78:81], v23 offset:4208
	ds_read_b128 v[82:85], v23 offset:8304
	ds_read_b128 v[86:89], v23 offset:12400
	ds_read_b128 v[90:93], v23 offset:16496
	s_waitcnt vmcnt(36) lgkmcnt(5)
	v_fmac_f32_e32 v4, v28, v156
	v_fmac_f32_e32 v5, v32, v156
	v_fmac_f32_e32 v12, v36, v156
	v_fmac_f32_e32 v13, v40, v156
	v_fmac_f32_e32 v22, v44, v156
	v_fmac_f32_e32 v4, v29, v157
	v_fmac_f32_e32 v5, v33, v157
	v_fmac_f32_e32 v12, v37, v157
	v_fmac_f32_e32 v13, v41, v157
	v_fmac_f32_e32 v22, v45, v157
	v_fmac_f32_e32 v4, v30, v158
	v_fmac_f32_e32 v5, v34, v158
	v_fmac_f32_e32 v12, v38, v158
	v_fmac_f32_e32 v13, v42, v158
	v_fmac_f32_e32 v22, v46, v158
	v_fmac_f32_e32 v4, v31, v159
	v_fmac_f32_e32 v5, v35, v159
	v_fmac_f32_e32 v12, v39, v159
	v_fmac_f32_e32 v13, v43, v159
	v_fmac_f32_e32 v22, v47, v159
	ds_read_b128 v[28:31], v23 offset:128
	ds_read_b128 v[32:35], v23 offset:4224
	ds_read_b128 v[36:39], v23 offset:8320
	ds_read_b128 v[40:43], v23 offset:12416
	ds_read_b128 v[44:47], v23 offset:16512
	s_waitcnt vmcnt(32) lgkmcnt(5)
	v_fmac_f32_e32 v4, v74, v160
	v_fmac_f32_e32 v5, v78, v160
	v_fmac_f32_e32 v12, v82, v160
	v_fmac_f32_e32 v13, v86, v160
	v_fmac_f32_e32 v22, v90, v160
	v_fmac_f32_e32 v4, v75, v161
	v_fmac_f32_e32 v5, v79, v161
	v_fmac_f32_e32 v12, v83, v161
	v_fmac_f32_e32 v13, v87, v161
	v_fmac_f32_e32 v22, v91, v161
	v_fmac_f32_e32 v4, v76, v162
	v_fmac_f32_e32 v5, v80, v162
	v_fmac_f32_e32 v12, v84, v162
	v_fmac_f32_e32 v13, v88, v162
	v_fmac_f32_e32 v22, v92, v162
	v_fmac_f32_e32 v4, v77, v163
	v_fmac_f32_e32 v5, v81, v163
	v_fmac_f32_e32 v12, v85, v163
	v_fmac_f32_e32 v13, v89, v163
	v_fmac_f32_e32 v22, v93, v163
	ds_read_b128 v[74:77], v23 offset:144
	ds_read_b128 v[78:81], v23 offset:4240
	ds_read_b128 v[82:85], v23 offset:8336
	ds_read_b128 v[86:89], v23 offset:12432
	ds_read_b128 v[90:93], v23 offset:16528
	s_waitcnt vmcnt(28) lgkmcnt(5)
	v_fmac_f32_e32 v4, v28, v164
	v_fmac_f32_e32 v5, v32, v164
	v_fmac_f32_e32 v12, v36, v164
	v_fmac_f32_e32 v13, v40, v164
	v_fmac_f32_e32 v22, v44, v164
	v_fmac_f32_e32 v4, v29, v165
	v_fmac_f32_e32 v5, v33, v165
	v_fmac_f32_e32 v12, v37, v165
	v_fmac_f32_e32 v13, v41, v165
	v_fmac_f32_e32 v22, v45, v165
	v_fmac_f32_e32 v4, v30, v166
	v_fmac_f32_e32 v5, v34, v166
	v_fmac_f32_e32 v12, v38, v166
	v_fmac_f32_e32 v13, v42, v166
	v_fmac_f32_e32 v22, v46, v166
	v_fmac_f32_e32 v4, v31, v167
	v_fmac_f32_e32 v5, v35, v167
	v_fmac_f32_e32 v12, v39, v167
	v_fmac_f32_e32 v13, v43, v167
	v_fmac_f32_e32 v22, v47, v167
	ds_read_b128 v[28:31], v23 offset:160
	ds_read_b128 v[32:35], v23 offset:4256
	ds_read_b128 v[36:39], v23 offset:8352
	ds_read_b128 v[40:43], v23 offset:12448
	ds_read_b128 v[44:47], v23 offset:16544
	s_waitcnt vmcnt(24) lgkmcnt(5)
	v_fmac_f32_e32 v4, v74, v168
	v_fmac_f32_e32 v5, v78, v168
	v_fmac_f32_e32 v12, v82, v168
	v_fmac_f32_e32 v13, v86, v168
	v_fmac_f32_e32 v22, v90, v168
	v_fmac_f32_e32 v4, v75, v169
	v_fmac_f32_e32 v5, v79, v169
	v_fmac_f32_e32 v12, v83, v169
	v_fmac_f32_e32 v13, v87, v169
	v_fmac_f32_e32 v22, v91, v169
	v_fmac_f32_e32 v4, v76, v170
	v_fmac_f32_e32 v5, v80, v170
	v_fmac_f32_e32 v12, v84, v170
	v_fmac_f32_e32 v13, v88, v170
	v_fmac_f32_e32 v22, v92, v170
	v_fmac_f32_e32 v4, v77, v171
	v_fmac_f32_e32 v5, v81, v171
	v_fmac_f32_e32 v12, v85, v171
	v_fmac_f32_e32 v13, v89, v171
	v_fmac_f32_e32 v22, v93, v171
	ds_read_b128 v[74:77], v23 offset:176
	ds_read_b128 v[78:81], v23 offset:4272
	ds_read_b128 v[82:85], v23 offset:8368
	ds_read_b128 v[86:89], v23 offset:12464
	ds_read_b128 v[90:93], v23 offset:16560
	s_waitcnt vmcnt(20) lgkmcnt(5)
	v_fmac_f32_e32 v4, v28, v172
	v_fmac_f32_e32 v5, v32, v172
	v_fmac_f32_e32 v12, v36, v172
	v_fmac_f32_e32 v13, v40, v172
	v_fmac_f32_e32 v22, v44, v172
	v_fmac_f32_e32 v4, v29, v173
	v_fmac_f32_e32 v5, v33, v173
	v_fmac_f32_e32 v12, v37, v173
	v_fmac_f32_e32 v13, v41, v173
	v_fmac_f32_e32 v22, v45, v173
	v_fmac_f32_e32 v4, v30, v174
	v_fmac_f32_e32 v5, v34, v174
	v_fmac_f32_e32 v12, v38, v174
	v_fmac_f32_e32 v13, v42, v174
	v_fmac_f32_e32 v22, v46, v174
	v_fmac_f32_e32 v4, v31, v175
	v_fmac_f32_e32 v5, v35, v175
	v_fmac_f32_e32 v12, v39, v175
	v_fmac_f32_e32 v13, v43, v175
	v_fmac_f32_e32 v22, v47, v175
	ds_read_b128 v[28:31], v23 offset:192
	ds_read_b128 v[32:35], v23 offset:4288
	ds_read_b128 v[36:39], v23 offset:8384
	ds_read_b128 v[40:43], v23 offset:12480
	ds_read_b128 v[44:47], v23 offset:16576
	s_waitcnt vmcnt(16) lgkmcnt(5)
	v_fmac_f32_e32 v4, v74, v176
	v_fmac_f32_e32 v5, v78, v176
	v_fmac_f32_e32 v12, v82, v176
	v_fmac_f32_e32 v13, v86, v176
	v_fmac_f32_e32 v22, v90, v176
	v_fmac_f32_e32 v4, v75, v177
	v_fmac_f32_e32 v5, v79, v177
	v_fmac_f32_e32 v12, v83, v177
	v_fmac_f32_e32 v13, v87, v177
	v_fmac_f32_e32 v22, v91, v177
	v_fmac_f32_e32 v4, v76, v178
	v_fmac_f32_e32 v5, v80, v178
	v_fmac_f32_e32 v12, v84, v178
	v_fmac_f32_e32 v13, v88, v178
	v_fmac_f32_e32 v22, v92, v178
	v_fmac_f32_e32 v4, v77, v179
	v_fmac_f32_e32 v5, v81, v179
	v_fmac_f32_e32 v12, v85, v179
	v_fmac_f32_e32 v13, v89, v179
	v_fmac_f32_e32 v22, v93, v179
	ds_read_b128 v[74:77], v23 offset:208
	ds_read_b128 v[78:81], v23 offset:4304
	ds_read_b128 v[82:85], v23 offset:8400
	ds_read_b128 v[86:89], v23 offset:12496
	ds_read_b128 v[90:93], v23 offset:16592
	s_waitcnt vmcnt(12) lgkmcnt(5)
	v_fmac_f32_e32 v4, v28, v180
	v_fmac_f32_e32 v5, v32, v180
	v_fmac_f32_e32 v12, v36, v180
	v_fmac_f32_e32 v13, v40, v180
	v_fmac_f32_e32 v22, v44, v180
	v_fmac_f32_e32 v4, v29, v181
	v_fmac_f32_e32 v5, v33, v181
	v_fmac_f32_e32 v12, v37, v181
	v_fmac_f32_e32 v13, v41, v181
	v_fmac_f32_e32 v22, v45, v181
	v_fmac_f32_e32 v4, v30, v182
	v_fmac_f32_e32 v5, v34, v182
	v_fmac_f32_e32 v12, v38, v182
	v_fmac_f32_e32 v13, v42, v182
	v_fmac_f32_e32 v22, v46, v182
	v_fmac_f32_e32 v4, v31, v183
	v_fmac_f32_e32 v5, v35, v183
	v_fmac_f32_e32 v12, v39, v183
	v_fmac_f32_e32 v13, v43, v183
	v_fmac_f32_e32 v22, v47, v183
	ds_read_b128 v[28:31], v23 offset:224
	ds_read_b128 v[32:35], v23 offset:4320
	ds_read_b128 v[36:39], v23 offset:8416
	ds_read_b128 v[40:43], v23 offset:12512
	ds_read_b128 v[44:47], v23 offset:16608
	s_waitcnt vmcnt(8) lgkmcnt(5)
	v_fmac_f32_e32 v4, v74, v184
	v_fmac_f32_e32 v5, v78, v184
	v_fmac_f32_e32 v12, v82, v184
	v_fmac_f32_e32 v13, v86, v184
	v_fmac_f32_e32 v22, v90, v184
	v_fmac_f32_e32 v4, v75, v185
	v_fmac_f32_e32 v5, v79, v185
	v_fmac_f32_e32 v12, v83, v185
	v_fmac_f32_e32 v13, v87, v185
	v_fmac_f32_e32 v22, v91, v185
	v_fmac_f32_e32 v4, v76, v186
	v_fmac_f32_e32 v5, v80, v186
	v_fmac_f32_e32 v12, v84, v186
	v_fmac_f32_e32 v13, v88, v186
	v_fmac_f32_e32 v22, v92, v186
	v_fmac_f32_e32 v4, v77, v187
	v_fmac_f32_e32 v5, v81, v187
	v_fmac_f32_e32 v12, v85, v187
	v_fmac_f32_e32 v13, v89, v187
	v_fmac_f32_e32 v22, v93, v187
	ds_read_b128 v[74:77], v23 offset:240
	ds_read_b128 v[78:81], v23 offset:4336
	ds_read_b128 v[82:85], v23 offset:8432
	ds_read_b128 v[86:89], v23 offset:12528
	ds_read_b128 v[90:93], v23 offset:16624
	s_waitcnt vmcnt(4) lgkmcnt(5)
	v_fmac_f32_e32 v4, v28, v192
	v_fmac_f32_e32 v5, v32, v192
	v_fmac_f32_e32 v12, v36, v192
	v_fmac_f32_e32 v13, v40, v192
	v_fmac_f32_e32 v22, v44, v192
	v_fmac_f32_e32 v4, v29, v193
	v_fmac_f32_e32 v5, v33, v193
	v_fmac_f32_e32 v12, v37, v193
	v_fmac_f32_e32 v13, v41, v193
	v_fmac_f32_e32 v22, v45, v193
	v_fmac_f32_e32 v4, v30, v194
	v_fmac_f32_e32 v5, v34, v194
	v_fmac_f32_e32 v12, v38, v194
	v_fmac_f32_e32 v13, v42, v194
	v_fmac_f32_e32 v22, v46, v194
	v_fmac_f32_e32 v4, v31, v195
	v_fmac_f32_e32 v5, v35, v195
	v_fmac_f32_e32 v12, v39, v195
	v_fmac_f32_e32 v13, v43, v195
	v_fmac_f32_e32 v22, v47, v195
	s_waitcnt vmcnt(0) lgkmcnt(0)
	v_fmac_f32_e32 v4, v74, v196
	v_fmac_f32_e32 v5, v78, v196
	v_fmac_f32_e32 v12, v82, v196
	v_fmac_f32_e32 v13, v86, v196
	v_fmac_f32_e32 v22, v90, v196
	v_fmac_f32_e32 v4, v75, v197
	v_fmac_f32_e32 v5, v79, v197
	v_fmac_f32_e32 v12, v83, v197
	v_fmac_f32_e32 v13, v87, v197
	v_fmac_f32_e32 v22, v91, v197
	v_fmac_f32_e32 v4, v76, v198
	v_fmac_f32_e32 v5, v80, v198
	v_fmac_f32_e32 v12, v84, v198
	v_fmac_f32_e32 v13, v88, v198
	v_fmac_f32_e32 v22, v92, v198
	v_fmac_f32_e32 v4, v77, v199
	v_fmac_f32_e32 v5, v81, v199
	v_fmac_f32_e32 v12, v85, v199
	v_fmac_f32_e32 v13, v89, v199
	v_fmac_f32_e32 v22, v93, v199
	v_mov_b32_e32 v2, v11
	v_mad_u64_u32 v[2:3], s[6:7], v0, 20, v[2:3]
	v_add_u32_e32 v3, 0x5000, v2
	s_movk_i32 s6, 0xa0
	ds_write2_b32 v3, v4, v5 offset1:1
	v_add_u32_e32 v3, 0x5008, v2
	v_cmp_gt_i32_e32 vcc, s6, v0
	ds_write2_b32 v3, v12, v13 offset1:1
	ds_write_b32 v2, v22 offset:20496
	s_waitcnt lgkmcnt(0)
	s_barrier
	s_and_saveexec_b64 s[6:7], vcc
	s_cbranch_execz .LBB0_23
	s_lshl_b32 s8, s39, 5
	v_or_b32_e32 v2, s8, v1
	v_ashrrev_i32_e32 v3, 31, v2
	v_lshl_add_u64 v[2:3], v[2:3], 2, s[50:51]
	global_load_dword v21, v[2:3], off
	v_lshlrev_b32_e32 v0, 2, v10
	v_mul_u32_u24_e32 v2, 20, v1
	s_movk_i32 s9, 0x1800
	v_mul_lo_u32 v3, v10, s9
	v_add3_u32 v0, 0, v0, v2
	v_add_u32_e32 v2, s8, v3
	v_add_u32_e32 v3, 0x5000, v0
	v_add_u32_e32 v4, 0x5400, v0
	v_add_u32_e32 v22, 0x5e00, v0
	v_add_u32_e32 v28, 0x6400, v0
	v_add_u32_e32 v30, 0x6800, v0
	v_add_u32_e32 v32, 0x6e00, v0
	v_add_u32_e32 v34, 0x7200, v0
	v_add_u32_e32 v10, 0x5a00, v0
	v_or_b32_e32 v0, v2, v1
	ds_read2_b32 v[2:3], v3 offset1:160
	ds_read2_b32 v[4:5], v4 offset0:64 offset1:224
	ds_read2_b32 v[12:13], v10 offset1:160
	ds_read2_b32 v[22:23], v22 offset0:64 offset1:224
	ds_read2_b32 v[28:29], v28 offset1:160
	ds_read2_b32 v[30:31], v30 offset0:64 offset1:224
	ds_read2_b32 v[32:33], v32 offset1:160
	ds_read2_b32 v[34:35], v34 offset0:64 offset1:224
	v_ashrrev_i32_e32 v1, 31, v0
	v_lshl_add_u64 v[0:1], v[0:1], 2, s[14:15]
	s_waitcnt vmcnt(0) lgkmcnt(7)
	v_add_f32_e32 v2, v21, v2
	v_add_f32_e32 v2, v2, v3
	s_waitcnt lgkmcnt(6)
	v_add_f32_e32 v2, v2, v4
	v_add_f32_e32 v2, v2, v5
	s_waitcnt lgkmcnt(5)
	v_add_f32_e32 v2, v2, v12
	v_add_f32_e32 v2, v2, v13
	s_waitcnt lgkmcnt(4)
	v_add_f32_e32 v2, v2, v22
	v_add_f32_e32 v2, v2, v23
	s_waitcnt lgkmcnt(3)
	v_add_f32_e32 v2, v2, v28
	v_add_f32_e32 v2, v2, v29
	s_waitcnt lgkmcnt(2)
	v_add_f32_e32 v2, v2, v30
	v_add_f32_e32 v2, v2, v31
	s_waitcnt lgkmcnt(1)
	v_add_f32_e32 v2, v2, v32
	v_add_f32_e32 v2, v2, v33
	s_waitcnt lgkmcnt(0)
	v_add_f32_e32 v2, v2, v34
	v_add_f32_e32 v2, v2, v35
	global_store_dword v[0:1], v2, off
	s_branch .LBB0_23
